# stack: lazy rescale + mask skip (paged MLA) + counted vmcnt and MFMA/VALU-interleaved fast path with lazy rescale in the prompt MLA tile loop
# speedup vs baseline: 1.0196x; 1.0054x over previous
.LBB0_1184:
	s_add_i32 s22, s67, 64
	v_cmp_le_i32_e64 s[22:23], s22, v173
	s_add_i32 s100, s67, 63
	v_cmp_gt_i32_e32 vcc, s100, v171
	s_and_b64 s[100:101], s[94:95], s[22:23]
	s_cbranch_vccnz .Lpa_A1_slow
	s_cmp_eq_u64 s[100:101], exec
	s_cbranch_scc0 .Lpa_A1_slow
	ds_read_b128 v[4:7], v175 offset:0
	ds_read_b128 v[82:85], v175 offset:6656
	ds_read_b128 v[8:11], v175 offset:32
	ds_read_b128 v[214:217], v175 offset:6688
	ds_read_b128 v[12:15], v175 offset:64
	ds_read_b128 v[218:221], v175 offset:6720
	ds_read_b128 v[188:191], v175 offset:96
	ds_read_b128 v[222:225], v175 offset:6752
	ds_read_b128 v[192:195], v175 offset:128
	ds_read_b128 v[226:229], v175 offset:6784
	ds_read_b128 v[210:213], v175 offset:160
	ds_read_b128 v[244:247], v175 offset:6816
	v_max_f32_e32 v3, v19, v19
	v_max_f32_e32 v232, v18, v18
	v_max_f32_e32 v3, v232, v3
	v_max3_f32 v3, v3, v20, v21
	v_max3_f32 v3, v3, v22, v23
	v_max3_f32 v3, v3, v24, v25
	v_max3_f32 v3, v3, v26, v27
	v_max3_f32 v3, v3, v28, v29
	v_and_b32_e32 v239, 64, v236
	v_max3_f32 v3, v3, v30, v31
	v_xor_b32_e32 v232, 32, v236
	v_max3_f32 v3, v3, v32, v33
	v_add_u32_e32 v239, 64, v239
	v_max3_f32 v3, v3, v34, v35
	v_cmp_lt_i32_e32 vcc, v232, v239
	v_max3_f32 v3, v3, v36, v37
	v_max3_f32 v3, v3, v38, v39
	v_max3_f32 v3, v3, v40, v41
	v_max3_f32 v3, v3, v42, v43
	v_max3_f32 v3, v3, v44, v45
	v_max3_f32 v3, v3, v46, v47
	v_max3_f32 v3, v3, v48, v49
	v_cndmask_b32_e32 v232, v236, v232, vcc
	v_lshlrev_b32_e32 v232, 2, v232
	ds_bpermute_b32 v232, v232, v3
	s_waitcnt lgkmcnt(0)
	v_max_f32_e32 v3, v3, v232
	v_mov_b32_e32 v233, 0x41000000
	v_sub_f32_e32 v232, v3, v186
	v_cmp_lt_f32_e64 s[100:101], v233, v232
	s_cmp_lg_u64 s[100:101], 0
	s_cbranch_scc1 .Lpa_A1_resc
	v_mov_b32_e32 v3, v186
	v_mov_b32_e32 v232, 1.0
.Lpa_A1_rjoin:
	v_mfma_f32_32x32x16_bf16 v[98:113], v[4:7], v[130:133], 0
	v_sub_f32_e32 v239, v18, v3
	v_exp_f32_e32 v18, v239
	v_sub_f32_e32 v17, v19, v3
	v_exp_f32_e32 v19, v17
	v_mfma_f32_32x32x16_bf16 v[82:97], v[82:85], v[130:133], 0
	v_sub_f32_e32 v17, v20, v3
	v_exp_f32_e32 v20, v17
	v_sub_f32_e32 v17, v21, v3
	v_exp_f32_e32 v21, v17
	v_mfma_f32_32x32x16_bf16 v[98:113], v[8:11], v[134:137], v[98:113]
	v_sub_f32_e32 v17, v22, v3
	v_add_f32_e32 v239, 0, v18
	v_exp_f32_e32 v22, v17
	v_sub_f32_e32 v17, v23, v3
	v_add_f32_e32 v239, v19, v239
	v_exp_f32_e32 v23, v17
	v_mfma_f32_32x32x16_bf16 v[82:97], v[214:217], v[134:137], v[82:97]
	v_sub_f32_e32 v17, v24, v3
	v_add_f32_e32 v239, v20, v239
	v_exp_f32_e32 v24, v17
	v_sub_f32_e32 v17, v25, v3
	v_add_f32_e32 v239, v21, v239
	v_exp_f32_e32 v25, v17
	v_mfma_f32_32x32x16_bf16 v[98:113], v[12:15], v[138:141], v[98:113]
	v_sub_f32_e32 v17, v26, v3
	v_add_f32_e32 v239, v22, v239
	v_exp_f32_e32 v26, v17
	v_sub_f32_e32 v17, v27, v3
	v_add_f32_e32 v239, v23, v239
	v_exp_f32_e32 v27, v17
	v_mfma_f32_32x32x16_bf16 v[82:97], v[218:221], v[138:141], v[82:97]
	v_sub_f32_e32 v17, v28, v3
	v_add_f32_e32 v239, v24, v239
	v_exp_f32_e32 v28, v17
	v_sub_f32_e32 v17, v29, v3
	v_add_f32_e32 v239, v25, v239
	v_exp_f32_e32 v29, v17
	v_mfma_f32_32x32x16_bf16 v[98:113], v[188:191], v[142:145], v[98:113]
	v_sub_f32_e32 v17, v30, v3
	v_add_f32_e32 v239, v26, v239
	v_exp_f32_e32 v30, v17
	v_sub_f32_e32 v17, v31, v3
	v_add_f32_e32 v239, v27, v239
	v_exp_f32_e32 v31, v17
	v_mfma_f32_32x32x16_bf16 v[82:97], v[222:225], v[142:145], v[82:97]
	v_sub_f32_e32 v17, v32, v3
	v_add_f32_e32 v239, v28, v239
	v_exp_f32_e32 v32, v17
	v_sub_f32_e32 v17, v33, v3
	v_add_f32_e32 v239, v29, v239
	v_exp_f32_e32 v33, v17
	v_mfma_f32_32x32x16_bf16 v[98:113], v[192:195], v[146:149], v[98:113]
	v_sub_f32_e32 v17, v34, v3
	v_add_f32_e32 v239, v30, v239
	v_exp_f32_e32 v34, v17
	v_mfma_f32_32x32x16_bf16 v[82:97], v[226:229], v[146:149], v[82:97]
	v_sub_f32_e32 v17, v35, v3
	v_add_f32_e32 v239, v31, v239
	v_exp_f32_e32 v35, v17
	v_mfma_f32_32x32x16_bf16 v[98:113], v[210:213], v[150:153], v[98:113]
	v_sub_f32_e32 v17, v36, v3
	v_add_f32_e32 v239, v32, v239
	v_exp_f32_e32 v36, v17
	v_mfma_f32_32x32x16_bf16 v[82:97], v[244:247], v[150:153], v[82:97]
	v_sub_f32_e32 v17, v37, v3
	v_add_f32_e32 v239, v33, v239
	v_exp_f32_e32 v37, v17
	ds_read_b64_tr_b16 v[4:5], v177 offset:0
	ds_read_b64_tr_b16 v[6:7], v177 offset:1536
	ds_read_b64_tr_b16 v[8:9], v177 offset:64
	ds_read_b64_tr_b16 v[10:11], v177 offset:1600
	ds_read_b64_tr_b16 v[12:13], v177 offset:3072
	ds_read_b64_tr_b16 v[14:15], v177 offset:4608
	ds_read_b64_tr_b16 v[188:189], v177 offset:3136
	ds_read_b64_tr_b16 v[190:191], v177 offset:4672
	ds_read_b64_tr_b16 v[192:193], v177 offset:6144
	ds_read_b64_tr_b16 v[194:195], v177 offset:7680
	ds_read_b64_tr_b16 v[210:211], v177 offset:6208
	ds_read_b64_tr_b16 v[212:213], v177 offset:7744
	ds_read_b64_tr_b16 v[214:215], v177 offset:9216
	ds_read_b64_tr_b16 v[216:217], v177 offset:10752
	ds_read_b64_tr_b16 v[218:219], v177 offset:9280
	ds_read_b64_tr_b16 v[220:221], v177 offset:10816
	v_sub_f32_e32 v17, v38, v3
	v_add_f32_e32 v239, v34, v239
	v_exp_f32_e32 v38, v17
	v_sub_f32_e32 v17, v39, v3
	v_add_f32_e32 v239, v35, v239
	v_exp_f32_e32 v39, v17
	v_sub_f32_e32 v17, v40, v3
	v_add_f32_e32 v239, v36, v239
	v_exp_f32_e32 v40, v17
	v_sub_f32_e32 v17, v41, v3
	v_add_f32_e32 v239, v37, v239
	v_exp_f32_e32 v41, v17
	v_cvt_pk_bf16_f32 v222, v18, v19
	v_cvt_pk_bf16_f32 v223, v20, v21
	v_cvt_pk_bf16_f32 v224, v22, v23
	v_cvt_pk_bf16_f32 v225, v24, v25
	v_cvt_pk_bf16_f32 v226, v26, v27
	v_cvt_pk_bf16_f32 v227, v28, v29
	v_cvt_pk_bf16_f32 v228, v30, v31
	v_cvt_pk_bf16_f32 v229, v32, v33
	v_cvt_pk_bf16_f32 v244, v34, v35
	v_cvt_pk_bf16_f32 v245, v36, v37
	v_cvt_pk_bf16_f32 v246, v38, v39
	v_cvt_pk_bf16_f32 v247, v40, v41
	s_waitcnt lgkmcnt(0)
	v_mfma_f32_32x32x16_bf16 v[66:81], v[4:7], v[222:225], v[66:81]
	v_sub_f32_e32 v17, v42, v3
	v_add_f32_e32 v239, v38, v239
	v_exp_f32_e32 v42, v17
	v_sub_f32_e32 v17, v43, v3
	v_add_f32_e32 v239, v39, v239
	v_exp_f32_e32 v43, v17
	v_mfma_f32_32x32x16_bf16 v[50:65], v[8:11], v[222:225], v[50:65]
	v_sub_f32_e32 v17, v44, v3
	v_add_f32_e32 v239, v40, v239
	v_exp_f32_e32 v44, v17
	v_sub_f32_e32 v17, v45, v3
	v_add_f32_e32 v239, v41, v239
	v_exp_f32_e32 v45, v17
	v_mfma_f32_32x32x16_bf16 v[66:81], v[12:15], v[226:229], v[66:81]
	v_sub_f32_e32 v17, v46, v3
	v_add_f32_e32 v239, v42, v239
	v_exp_f32_e32 v46, v17
	v_sub_f32_e32 v17, v47, v3
	v_add_f32_e32 v239, v43, v239
	v_exp_f32_e32 v47, v17
	v_mfma_f32_32x32x16_bf16 v[50:65], v[188:191], v[226:229], v[50:65]
	v_sub_f32_e32 v17, v48, v3
	v_add_f32_e32 v239, v44, v239
	v_exp_f32_e32 v48, v17
	v_sub_f32_e32 v17, v49, v3
	v_add_f32_e32 v239, v45, v239
	v_exp_f32_e32 v49, v17
	v_mfma_f32_32x32x16_bf16 v[66:81], v[192:195], v[244:247], v[66:81]
	v_add_f32_e32 v239, v46, v239
	v_add_f32_e32 v239, v47, v239
	v_add_f32_e32 v239, v48, v239
	v_add_f32_e32 v16, v49, v239
	v_fmac_f32_e32 v16, v185, v232
	v_mov_b32_e32 v185, v16
	v_mov_b32_e32 v186, v3
	v_mfma_f32_32x32x16_bf16 v[50:65], v[210:213], v[244:247], v[50:65]
	v_cvt_pk_bf16_f32 v248, v42, v43
	v_cvt_pk_bf16_f32 v249, v44, v45
	v_cvt_pk_bf16_f32 v250, v46, v47
	v_cvt_pk_bf16_f32 v251, v48, v49
	s_nop 1
	v_mfma_f32_32x32x16_bf16 v[66:81], v[214:217], v[248:251], v[66:81]
	v_mfma_f32_32x32x16_bf16 v[50:65], v[218:221], v[248:251], v[50:65]
	s_branch .LBB0_1194
.Lpa_A1_resc:
	v_max_f32_e32 v3, v186, v3
	v_sub_f32_e32 v232, v186, v3
	v_exp_f32_e32 v232, v232
	s_nop 0
	v_pk_mul_f32 v[80:81], v[80:81], v[232:233] op_sel_hi:[1,0]
	v_pk_mul_f32 v[78:79], v[78:79], v[232:233] op_sel_hi:[1,0]
	v_pk_mul_f32 v[76:77], v[76:77], v[232:233] op_sel_hi:[1,0]
	v_pk_mul_f32 v[74:75], v[74:75], v[232:233] op_sel_hi:[1,0]
	v_pk_mul_f32 v[72:73], v[72:73], v[232:233] op_sel_hi:[1,0]
	v_pk_mul_f32 v[70:71], v[70:71], v[232:233] op_sel_hi:[1,0]
	v_pk_mul_f32 v[68:69], v[68:69], v[232:233] op_sel_hi:[1,0]
	v_pk_mul_f32 v[66:67], v[66:67], v[232:233] op_sel_hi:[1,0]
	v_pk_mul_f32 v[64:65], v[64:65], v[232:233] op_sel_hi:[1,0]
	v_pk_mul_f32 v[62:63], v[62:63], v[232:233] op_sel_hi:[1,0]
	v_pk_mul_f32 v[60:61], v[60:61], v[232:233] op_sel_hi:[1,0]
	v_pk_mul_f32 v[58:59], v[58:59], v[232:233] op_sel_hi:[1,0]
	v_pk_mul_f32 v[56:57], v[56:57], v[232:233] op_sel_hi:[1,0]
	v_pk_mul_f32 v[54:55], v[54:55], v[232:233] op_sel_hi:[1,0]
	v_pk_mul_f32 v[52:53], v[52:53], v[232:233] op_sel_hi:[1,0]
	v_pk_mul_f32 v[50:51], v[50:51], v[232:233] op_sel_hi:[1,0]
	s_branch .Lpa_A1_rjoin

.LBB0_1194:
	s_or_b64 exec, exec, s[24:25]
	s_add_i32 s100, s30, 3
	s_cmp_lt_u32 s100, s65
	s_cbranch_scc0 .LpvA1_drain
	s_cmp_eq_u64 s[18:19], 0
	s_cbranch_scc1 .LpvA1_two
	s_waitcnt vmcnt(3)
	s_branch .LpvA1_done
.LpvA1_two:
	s_waitcnt vmcnt(2)
	s_branch .LpvA1_done

.LpvA1_done:
	v_cndmask_b32_e64 v3, 0, 1, s[0:1]
	v_cmp_ne_u32_e64 s[24:25], 1, v3
	s_andn2_b64 vcc, exec, s[0:1]
	s_cbranch_vccnz .LBB0_1200
	s_and_saveexec_b64 s[0:1], s[16:17]
	s_cbranch_execz .LBB0_1197
	v_add_u32_e32 v3, v181, v182
	ds_write_b128 v3, v[122:125]
.LBB0_1197:
	s_or_b64 exec, exec, s[0:1]
	s_and_saveexec_b64 s[0:1], s[18:19]
	s_cbranch_execz .LBB0_1199
	v_add_u32_e32 v3, v183, v184
	ds_write_b128 v3, v[126:129]

.LBB0_1200:
	s_add_i32 s26, s30, 3
	s_cmp_lt_u32 s26, s65
	s_cselect_b64 s[0:1], -1, 0
	s_cmp_ge_u32 s26, s65
	ds_write_b128 v170, v[154:157] offset:38912
	s_waitcnt lgkmcnt(0)
	s_barrier
	s_cbranch_scc1 .LBB0_1218
	s_add_i32 s26, s30, 4
	s_cmp_ge_u32 s26, s65
	s_cbranch_scc1 .LBB0_1207
	s_and_saveexec_b64 s[26:27], s[16:17]
	s_cbranch_execz .LBB0_1204
	v_add_u32_e32 v3, s67, v179
	v_add_u32_e32 v3, 0x100, v3
	v_mad_i64_i32 v[4:5], s[28:29], v3, s70, v[166:167]
	global_load_dwordx4 v[122:125], v[4:5], off

.LBB0_1219:
	s_add_i32 s100, s67, 128
	v_cmp_le_i32_e32 vcc, s100, v173
	s_add_i32 s101, s67, 127
	s_and_b64 vcc, s[94:95], vcc
	s_cmp_eq_u64 vcc, exec
	s_cbranch_scc0 .Lpa_A2_slow
	v_cmp_gt_i32_e32 vcc, s101, v171
	s_cbranch_vccnz .Lpa_A2_slow
	ds_read_b128 v[4:7], v174 offset:0
	ds_read_b128 v[34:37], v174 offset:6656
	ds_read_b128 v[8:11], v174 offset:32
	ds_read_b128 v[214:217], v174 offset:6688
	ds_read_b128 v[12:15], v174 offset:64
	ds_read_b128 v[218:221], v174 offset:6720
	ds_read_b128 v[188:191], v174 offset:96
	ds_read_b128 v[222:225], v174 offset:6752
	ds_read_b128 v[192:195], v174 offset:128
	ds_read_b128 v[226:229], v174 offset:6784
	ds_read_b128 v[210:213], v174 offset:160
	ds_read_b128 v[244:247], v174 offset:6816
	v_max_f32_e32 v3, v99, v99
	v_max_f32_e32 v232, v98, v98
	v_max_f32_e32 v3, v232, v3
	v_max3_f32 v3, v3, v100, v101
	v_max3_f32 v3, v3, v102, v103
	v_max3_f32 v3, v3, v104, v105
	v_max3_f32 v3, v3, v106, v107
	v_max3_f32 v3, v3, v108, v109
	v_and_b32_e32 v239, 64, v236
	v_max3_f32 v3, v3, v110, v111
	v_xor_b32_e32 v232, 32, v236
	v_max3_f32 v3, v3, v112, v113
	v_add_u32_e32 v239, 64, v239
	v_max3_f32 v3, v3, v82, v83
	v_cmp_lt_i32_e32 vcc, v232, v239
	v_max3_f32 v3, v3, v84, v85
	v_max3_f32 v3, v3, v86, v87
	v_max3_f32 v3, v3, v88, v89
	v_max3_f32 v3, v3, v90, v91
	v_max3_f32 v3, v3, v92, v93
	v_max3_f32 v3, v3, v94, v95
	v_max3_f32 v3, v3, v96, v97
	v_cndmask_b32_e32 v232, v236, v232, vcc
	v_lshlrev_b32_e32 v232, 2, v232
	ds_bpermute_b32 v232, v232, v3
	s_waitcnt lgkmcnt(0)
	v_max_f32_e32 v3, v3, v232
	v_mov_b32_e32 v233, 0x41000000
	v_sub_f32_e32 v232, v3, v186
	v_cmp_lt_f32_e64 s[100:101], v233, v232
	s_cmp_lg_u64 s[100:101], 0
	s_cbranch_scc1 .Lpa_A2_resc
	v_mov_b32_e32 v3, v186
	v_mov_b32_e32 v232, 1.0
.Lpa_A2_rjoin:
	v_mfma_f32_32x32x16_bf16 v[18:33], v[4:7], v[130:133], 0
	v_sub_f32_e32 v239, v98, v3
	v_exp_f32_e32 v98, v239
	v_sub_f32_e32 v17, v99, v3
	v_exp_f32_e32 v99, v17
	v_mfma_f32_32x32x16_bf16 v[34:49], v[34:37], v[130:133], 0
	v_sub_f32_e32 v17, v100, v3
	v_exp_f32_e32 v100, v17
	v_sub_f32_e32 v17, v101, v3
	v_exp_f32_e32 v101, v17
	v_mfma_f32_32x32x16_bf16 v[18:33], v[8:11], v[134:137], v[18:33]
	v_sub_f32_e32 v17, v102, v3
	v_add_f32_e32 v239, 0, v98
	v_exp_f32_e32 v102, v17
	v_sub_f32_e32 v17, v103, v3
	v_add_f32_e32 v239, v99, v239
	v_exp_f32_e32 v103, v17
	v_mfma_f32_32x32x16_bf16 v[34:49], v[214:217], v[134:137], v[34:49]
	v_sub_f32_e32 v17, v104, v3
	v_add_f32_e32 v239, v100, v239
	v_exp_f32_e32 v104, v17
	v_sub_f32_e32 v17, v105, v3
	v_add_f32_e32 v239, v101, v239
	v_exp_f32_e32 v105, v17
	v_mfma_f32_32x32x16_bf16 v[18:33], v[12:15], v[138:141], v[18:33]
	v_sub_f32_e32 v17, v106, v3
	v_add_f32_e32 v239, v102, v239
	v_exp_f32_e32 v106, v17
	v_sub_f32_e32 v17, v107, v3
	v_add_f32_e32 v239, v103, v239
	v_exp_f32_e32 v107, v17
	v_mfma_f32_32x32x16_bf16 v[34:49], v[218:221], v[138:141], v[34:49]
	v_sub_f32_e32 v17, v108, v3
	v_add_f32_e32 v239, v104, v239
	v_exp_f32_e32 v108, v17
	v_sub_f32_e32 v17, v109, v3
	v_add_f32_e32 v239, v105, v239
	v_exp_f32_e32 v109, v17
	v_mfma_f32_32x32x16_bf16 v[18:33], v[188:191], v[142:145], v[18:33]
	v_sub_f32_e32 v17, v110, v3
	v_add_f32_e32 v239, v106, v239
	v_exp_f32_e32 v110, v17
	v_sub_f32_e32 v17, v111, v3
	v_add_f32_e32 v239, v107, v239
	v_exp_f32_e32 v111, v17
	v_mfma_f32_32x32x16_bf16 v[34:49], v[222:225], v[142:145], v[34:49]
	v_sub_f32_e32 v17, v112, v3
	v_add_f32_e32 v239, v108, v239
	v_exp_f32_e32 v112, v17
	v_sub_f32_e32 v17, v113, v3
	v_add_f32_e32 v239, v109, v239
	v_exp_f32_e32 v113, v17
	v_mfma_f32_32x32x16_bf16 v[18:33], v[192:195], v[146:149], v[18:33]
	v_sub_f32_e32 v17, v82, v3
	v_add_f32_e32 v239, v110, v239
	v_exp_f32_e32 v82, v17
	v_mfma_f32_32x32x16_bf16 v[34:49], v[226:229], v[146:149], v[34:49]
	v_sub_f32_e32 v17, v83, v3
	v_add_f32_e32 v239, v111, v239
	v_exp_f32_e32 v83, v17
	v_mfma_f32_32x32x16_bf16 v[18:33], v[210:213], v[150:153], v[18:33]
	v_sub_f32_e32 v17, v84, v3
	v_add_f32_e32 v239, v112, v239
	v_exp_f32_e32 v84, v17
	v_mfma_f32_32x32x16_bf16 v[34:49], v[244:247], v[150:153], v[34:49]
	v_sub_f32_e32 v17, v85, v3
	v_add_f32_e32 v239, v113, v239
	v_exp_f32_e32 v85, v17
	ds_read_b64_tr_b16 v[4:5], v178 offset:0
	ds_read_b64_tr_b16 v[6:7], v178 offset:1536
	ds_read_b64_tr_b16 v[8:9], v178 offset:64
	ds_read_b64_tr_b16 v[10:11], v178 offset:1600
	ds_read_b64_tr_b16 v[12:13], v178 offset:3072
	ds_read_b64_tr_b16 v[14:15], v178 offset:4608
	ds_read_b64_tr_b16 v[188:189], v178 offset:3136
	ds_read_b64_tr_b16 v[190:191], v178 offset:4672
	ds_read_b64_tr_b16 v[192:193], v178 offset:6144
	ds_read_b64_tr_b16 v[194:195], v178 offset:7680
	ds_read_b64_tr_b16 v[210:211], v178 offset:6208
	ds_read_b64_tr_b16 v[212:213], v178 offset:7744
	ds_read_b64_tr_b16 v[214:215], v178 offset:9216
	ds_read_b64_tr_b16 v[216:217], v178 offset:10752
	ds_read_b64_tr_b16 v[218:219], v178 offset:9280
	ds_read_b64_tr_b16 v[220:221], v178 offset:10816
	v_sub_f32_e32 v17, v86, v3
	v_add_f32_e32 v239, v82, v239
	v_exp_f32_e32 v86, v17
	v_sub_f32_e32 v17, v87, v3
	v_add_f32_e32 v239, v83, v239
	v_exp_f32_e32 v87, v17
	v_sub_f32_e32 v17, v88, v3
	v_add_f32_e32 v239, v84, v239
	v_exp_f32_e32 v88, v17
	v_sub_f32_e32 v17, v89, v3
	v_add_f32_e32 v239, v85, v239
	v_exp_f32_e32 v89, v17
	v_cvt_pk_bf16_f32 v222, v98, v99
	v_cvt_pk_bf16_f32 v223, v100, v101
	v_cvt_pk_bf16_f32 v224, v102, v103
	v_cvt_pk_bf16_f32 v225, v104, v105
	v_cvt_pk_bf16_f32 v226, v106, v107
	v_cvt_pk_bf16_f32 v227, v108, v109
	v_cvt_pk_bf16_f32 v228, v110, v111
	v_cvt_pk_bf16_f32 v229, v112, v113
	v_cvt_pk_bf16_f32 v244, v82, v83
	v_cvt_pk_bf16_f32 v245, v84, v85
	v_cvt_pk_bf16_f32 v246, v86, v87
	v_cvt_pk_bf16_f32 v247, v88, v89
	s_waitcnt lgkmcnt(0)
	v_mfma_f32_32x32x16_bf16 v[66:81], v[4:7], v[222:225], v[66:81]
	v_sub_f32_e32 v17, v90, v3
	v_add_f32_e32 v239, v86, v239
	v_exp_f32_e32 v90, v17
	v_sub_f32_e32 v17, v91, v3
	v_add_f32_e32 v239, v87, v239
	v_exp_f32_e32 v91, v17
	v_mfma_f32_32x32x16_bf16 v[50:65], v[8:11], v[222:225], v[50:65]
	v_sub_f32_e32 v17, v92, v3
	v_add_f32_e32 v239, v88, v239
	v_exp_f32_e32 v92, v17
	v_sub_f32_e32 v17, v93, v3
	v_add_f32_e32 v239, v89, v239
	v_exp_f32_e32 v93, v17
	v_mfma_f32_32x32x16_bf16 v[66:81], v[12:15], v[226:229], v[66:81]
	v_sub_f32_e32 v17, v94, v3
	v_add_f32_e32 v239, v90, v239
	v_exp_f32_e32 v94, v17
	v_sub_f32_e32 v17, v95, v3
	v_add_f32_e32 v239, v91, v239
	v_exp_f32_e32 v95, v17
	v_mfma_f32_32x32x16_bf16 v[50:65], v[188:191], v[226:229], v[50:65]
	v_sub_f32_e32 v17, v96, v3
	v_add_f32_e32 v239, v92, v239
	v_exp_f32_e32 v96, v17
	v_sub_f32_e32 v17, v97, v3
	v_add_f32_e32 v239, v93, v239
	v_exp_f32_e32 v97, v17
	v_mfma_f32_32x32x16_bf16 v[66:81], v[192:195], v[244:247], v[66:81]
	v_add_f32_e32 v239, v94, v239
	v_add_f32_e32 v239, v95, v239
	v_add_f32_e32 v239, v96, v239
	v_add_f32_e32 v16, v97, v239
	v_fmac_f32_e32 v16, v185, v232
	v_mov_b32_e32 v185, v16
	v_mov_b32_e32 v186, v3
	v_mfma_f32_32x32x16_bf16 v[50:65], v[210:213], v[244:247], v[50:65]
	v_cvt_pk_bf16_f32 v248, v90, v91
	v_cvt_pk_bf16_f32 v249, v92, v93
	v_cvt_pk_bf16_f32 v250, v94, v95
	v_cvt_pk_bf16_f32 v251, v96, v97
	s_nop 1
	v_mfma_f32_32x32x16_bf16 v[66:81], v[214:217], v[248:251], v[66:81]
	v_mfma_f32_32x32x16_bf16 v[50:65], v[218:221], v[248:251], v[50:65]
	s_branch .LBB0_1217

.LBB0_1223:
	s_add_i32 s100, s30, 4
	s_cmp_lt_u32 s100, s65
	s_cbranch_scc0 .LpvA2_drain
	s_cmp_eq_u64 s[18:19], 0
	s_cbranch_scc1 .LpvA2_two
	s_waitcnt vmcnt(3)
	s_branch .LpvA2_done

.LpvA2_drain:
	s_waitcnt vmcnt(0)
.LpvA2_done:
	s_andn2_b64 vcc, exec, s[0:1]
	s_cbranch_vccnz .LBB0_1229
	s_and_saveexec_b64 s[0:1], s[16:17]
	v_add_u32_e32 v3, v181, v182
	ds_write_b128 v3, v[114:117] offset:13312
	s_or_b64 exec, exec, s[0:1]
	s_and_saveexec_b64 s[0:1], s[18:19]
	v_add_u32_e32 v3, v183, v184
	ds_write_b128 v3, v[118:121] offset:13312
	s_or_b64 exec, exec, s[0:1]

.LmaskB:
	s_and_b64 s[48:49], s[14:15], s[74:75]
	v_cndmask_b32_e64 v147, v3, v238, s[48:49]
	s_and_b64 s[48:49], s[16:17], s[74:75]
	v_cndmask_b32_e64 v8, v8, v238, s[48:49]
	s_and_b64 s[48:49], s[18:19], s[74:75]
	v_cndmask_b32_e64 v9, v9, v238, s[48:49]
	s_and_b64 s[48:49], s[20:21], s[74:75]
	v_cndmask_b32_e64 v10, v10, v238, s[48:49]
	s_and_b64 s[48:49], s[22:23], s[74:75]
	v_cndmask_b32_e64 v11, v11, v238, s[48:49]
	s_and_b64 s[48:49], s[24:25], s[74:75]
	v_cndmask_b32_e64 v12, v12, v238, s[48:49]
	s_and_b64 s[48:49], s[26:27], s[74:75]
	v_cndmask_b32_e64 v13, v13, v238, s[48:49]
	s_and_b64 s[48:49], s[28:29], s[74:75]
	v_cndmask_b32_e64 v14, v14, v238, s[48:49]
	s_and_b64 s[48:49], s[30:31], s[74:75]
	v_cndmask_b32_e64 v4, v4, v238, s[48:49]
	s_and_b64 s[48:49], s[34:35], s[74:75]
	v_cndmask_b32_e64 v5, v5, v238, s[48:49]
	s_and_b64 s[48:49], s[36:37], s[74:75]
	v_cndmask_b32_e64 v6, v6, v238, s[48:49]
	s_and_b64 s[48:49], s[38:39], s[74:75]
	v_cndmask_b32_e64 v7, v7, v238, s[48:49]
	s_and_b64 s[48:49], s[40:41], s[74:75]
	v_cndmask_b32_e64 v15, v15, v238, s[48:49]
	s_and_b64 s[48:49], s[42:43], s[74:75]
	v_cndmask_b32_e64 v16, v16, v238, s[48:49]
	s_and_b64 s[48:49], s[44:45], s[74:75]
	v_cndmask_b32_e64 v17, v17, v238, s[48:49]
	s_and_b64 s[48:49], s[46:47], s[74:75]
	v_cndmask_b32_e64 v146, v146, v238, s[48:49]
	s_branch .LmaskB_join
.LBB0_1545:
	v_and_b32_e32 v4, 64, v236
	v_xor_b32_e32 v3, 32, v236
	v_add_u32_e32 v4, 64, v4
	v_cmp_lt_i32_e32 vcc, v3, v4
	s_lshl_b64 s[8:9], s[82:83], 4
	s_lshl_b32 s14, s94, 1
	v_cndmask_b32_e32 v3, v236, v3, vcc
	s_or_b32 s8, s8, s14
	v_ashrrev_i32_e32 v165, 31, v164
	v_lshlrev_b32_e32 v3, 2, v3
	v_lshl_add_u64 v[6:7], s[8:9], 0, v[164:165]
	v_ashrrev_i32_e32 v163, 31, v162
	s_movk_i32 s14, 0x60
	ds_bpermute_b32 v3, v3, v1
	v_mad_u64_u32 v[4:5], s[8:9], v6, s14, v[162:163]
	v_mad_i32_i24 v5, v7, s14, v5
	v_lshlrev_b64 v[6:7], 10, v[4:5]
	v_lshl_add_u64 v[6:7], s[62:63], 0, v[6:7]
	v_mov_b32_e32 v175, v2
	v_lshl_add_u64 v[6:7], v[6:7], 0, v[174:175]
	v_cmp_gt_u32_e32 vcc, 32, v168
	global_store_dwordx4 v[6:7], v[130:133], off
	global_store_dwordx4 v[6:7], v[134:137], off offset:32
	global_store_dwordx4 v[6:7], v[138:141], off offset:64
	global_store_dwordx4 v[6:7], v[142:145], off offset:96
	global_store_dwordx4 v[6:7], v[114:117], off offset:128
	global_store_dwordx4 v[6:7], v[118:121], off offset:160
	global_store_dwordx4 v[6:7], v[122:125], off offset:192
	global_store_dwordx4 v[6:7], v[126:129], off offset:224
	global_store_dwordx4 v[6:7], v[98:101], off offset:256
	global_store_dwordx4 v[6:7], v[102:105], off offset:288
	global_store_dwordx4 v[6:7], v[106:109], off offset:320
	global_store_dwordx4 v[6:7], v[110:113], off offset:352
	global_store_dwordx4 v[6:7], v[82:85], off offset:384
	global_store_dwordx4 v[6:7], v[86:89], off offset:416
	global_store_dwordx4 v[6:7], v[90:93], off offset:448
	global_store_dwordx4 v[6:7], v[94:97], off offset:480
	global_store_dwordx4 v[6:7], v[66:69], off offset:512
	global_store_dwordx4 v[6:7], v[70:73], off offset:544
	global_store_dwordx4 v[6:7], v[74:77], off offset:576
	global_store_dwordx4 v[6:7], v[78:81], off offset:608
	global_store_dwordx4 v[6:7], v[50:53], off offset:640
	global_store_dwordx4 v[6:7], v[54:57], off offset:672
	global_store_dwordx4 v[6:7], v[58:61], off offset:704
	global_store_dwordx4 v[6:7], v[62:65], off offset:736
	global_store_dwordx4 v[6:7], v[34:37], off offset:768
	global_store_dwordx4 v[6:7], v[38:41], off offset:800
	global_store_dwordx4 v[6:7], v[42:45], off offset:832
	global_store_dwordx4 v[6:7], v[46:49], off offset:864
	global_store_dwordx4 v[6:7], v[18:21], off offset:896
	global_store_dwordx4 v[6:7], v[22:25], off offset:928
	global_store_dwordx4 v[6:7], v[26:29], off offset:960
	global_store_dwordx4 v[6:7], v[30:33], off offset:992
	s_and_saveexec_b64 s[8:9], vcc
	s_cbranch_execz .LBB0_1547
	s_waitcnt lgkmcnt(0)
	v_add_f32_e32 v167, v1, v3
	v_lshl_add_u64 v[4:5], v[4:5], 3, s[80:81]
	global_store_dwordx2 v[4:5], v[166:167], off

.LBB0_1637:
	s_add_i32 s22, s67, 64
	v_cmp_le_i32_e64 s[22:23], s22, v173
	s_add_i32 s100, s67, 63
	v_cmp_gt_i32_e32 vcc, s100, v171
	s_and_b64 s[100:101], s[74:75], s[22:23]
	s_cbranch_vccnz .Lpa_B1_slow
	s_cmp_eq_u64 s[100:101], exec
	s_cbranch_scc0 .Lpa_B1_slow
	ds_read_b128 v[4:7], v175 offset:0
	ds_read_b128 v[82:85], v175 offset:6656
	ds_read_b128 v[8:11], v175 offset:32
	ds_read_b128 v[214:217], v175 offset:6688
	ds_read_b128 v[12:15], v175 offset:64
	ds_read_b128 v[218:221], v175 offset:6720
	ds_read_b128 v[188:191], v175 offset:96
	ds_read_b128 v[222:225], v175 offset:6752
	ds_read_b128 v[192:195], v175 offset:128
	ds_read_b128 v[226:229], v175 offset:6784
	ds_read_b128 v[210:213], v175 offset:160
	ds_read_b128 v[244:247], v175 offset:6816
	v_max_f32_e32 v3, v19, v19
	v_max_f32_e32 v232, v18, v18
	v_max_f32_e32 v3, v232, v3
	v_max3_f32 v3, v3, v20, v21
	v_max3_f32 v3, v3, v22, v23
	v_max3_f32 v3, v3, v24, v25
	v_max3_f32 v3, v3, v26, v27
	v_max3_f32 v3, v3, v28, v29
	v_and_b32_e32 v239, 64, v236
	v_max3_f32 v3, v3, v30, v31
	v_xor_b32_e32 v232, 32, v236
	v_max3_f32 v3, v3, v32, v33
	v_add_u32_e32 v239, 64, v239
	v_max3_f32 v3, v3, v34, v35
	v_cmp_lt_i32_e32 vcc, v232, v239
	v_max3_f32 v3, v3, v36, v37
	v_max3_f32 v3, v3, v38, v39
	v_max3_f32 v3, v3, v40, v41
	v_max3_f32 v3, v3, v42, v43
	v_max3_f32 v3, v3, v44, v45
	v_max3_f32 v3, v3, v46, v47
	v_max3_f32 v3, v3, v48, v49
	v_cndmask_b32_e32 v232, v236, v232, vcc
	v_lshlrev_b32_e32 v232, 2, v232
	ds_bpermute_b32 v232, v232, v3
	s_waitcnt lgkmcnt(0)
	v_max_f32_e32 v3, v3, v232
	v_mov_b32_e32 v233, 0x41000000
	v_sub_f32_e32 v232, v3, v186
	v_cmp_lt_f32_e64 s[100:101], v233, v232
	s_cmp_lg_u64 s[100:101], 0
	s_cbranch_scc1 .Lpa_B1_resc
	v_mov_b32_e32 v3, v186
	v_mov_b32_e32 v232, 1.0

.LBB0_1672:
	s_add_i32 s100, s67, 128
	v_cmp_le_i32_e32 vcc, s100, v173
	s_add_i32 s101, s67, 127
	s_and_b64 vcc, s[74:75], vcc
	s_cmp_eq_u64 vcc, exec
	s_cbranch_scc0 .Lpa_B2_slow
	v_cmp_gt_i32_e32 vcc, s101, v171
	s_cbranch_vccnz .Lpa_B2_slow
	ds_read_b128 v[4:7], v174 offset:0
	ds_read_b128 v[34:37], v174 offset:6656
	ds_read_b128 v[8:11], v174 offset:32
	ds_read_b128 v[214:217], v174 offset:6688
	ds_read_b128 v[12:15], v174 offset:64
	ds_read_b128 v[218:221], v174 offset:6720
	ds_read_b128 v[188:191], v174 offset:96
	ds_read_b128 v[222:225], v174 offset:6752
	ds_read_b128 v[192:195], v174 offset:128
	ds_read_b128 v[226:229], v174 offset:6784
	ds_read_b128 v[210:213], v174 offset:160
	ds_read_b128 v[244:247], v174 offset:6816
	v_max_f32_e32 v3, v99, v99
	v_max_f32_e32 v232, v98, v98
	v_max_f32_e32 v3, v232, v3
	v_max3_f32 v3, v3, v100, v101
	v_max3_f32 v3, v3, v102, v103
	v_max3_f32 v3, v3, v104, v105
	v_max3_f32 v3, v3, v106, v107
	v_max3_f32 v3, v3, v108, v109
	v_and_b32_e32 v239, 64, v236
	v_max3_f32 v3, v3, v110, v111
	v_xor_b32_e32 v232, 32, v236
	v_max3_f32 v3, v3, v112, v113
	v_add_u32_e32 v239, 64, v239
	v_max3_f32 v3, v3, v82, v83
	v_cmp_lt_i32_e32 vcc, v232, v239
	v_max3_f32 v3, v3, v84, v85
	v_max3_f32 v3, v3, v86, v87
	v_max3_f32 v3, v3, v88, v89
	v_max3_f32 v3, v3, v90, v91
	v_max3_f32 v3, v3, v92, v93
	v_max3_f32 v3, v3, v94, v95
	v_max3_f32 v3, v3, v96, v97
	v_cndmask_b32_e32 v232, v236, v232, vcc
	v_lshlrev_b32_e32 v232, 2, v232
	ds_bpermute_b32 v232, v232, v3
	s_waitcnt lgkmcnt(0)
	v_max_f32_e32 v3, v3, v232
	v_mov_b32_e32 v233, 0x41000000
	v_sub_f32_e32 v232, v3, v186
	v_cmp_lt_f32_e64 s[100:101], v233, v232
	s_cmp_lg_u64 s[100:101], 0
	s_cbranch_scc1 .Lpa_B2_resc
	v_mov_b32_e32 v3, v186
	v_mov_b32_e32 v232, 1.0

.LpvB2_drain:
	s_waitcnt vmcnt(0)
.LpvB2_done:
	s_andn2_b64 vcc, exec, s[0:1]
	s_cbranch_vccnz .LBB0_1682
	s_and_saveexec_b64 s[0:1], s[16:17]
	v_add_u32_e32 v3, v181, v182
	ds_write_b128 v3, v[114:117] offset:13312
	s_or_b64 exec, exec, s[0:1]
	s_and_saveexec_b64 s[0:1], s[18:19]
	v_add_u32_e32 v3, v183, v184
	ds_write_b128 v3, v[118:121] offset:13312
	s_or_b64 exec, exec, s[0:1]
